# mixer residual epilogue: 4 residual-row loads per group issued before one wait (was 2+2); on top of v39
# baseline (speedup 1.0000x reference)
.LBB0_1057:
	v_ashrrev_i32_e32 v199, 31, v198
	s_waitcnt vmcnt(0)
	global_load_dwordx4 v[218:221], v[186:187], off
	global_load_dwordx4 v[222:225], v[186:187], off offset:16
	v_lshlrev_b64 v[154:155], 12, v[198:199]
	v_ashrrev_i32_e32 v201, 31, v200
	v_lshl_add_u64 v[154:155], v[226:227], 0, v[154:155]
	v_ashrrev_i32_e32 v195, 31, v194
	v_lshlrev_b64 v[150:151], 12, v[200:201]
	flat_load_dwordx4 v[158:161], v[154:155]
	v_lshlrev_b64 v[154:155], 12, v[194:195]
	v_lshl_add_u64 v[146:147], v[226:227], 0, v[214:215]
	v_lshl_add_u64 v[150:151], v[226:227], 0, v[150:151]
	v_lshl_add_u64 v[154:155], v[226:227], 0, v[154:155]
	flat_load_dwordx4 v[146:149], v[146:147]
	flat_load_dwordx4 v[150:153], v[150:151]
	flat_load_dwordx4 v[182:185], v[154:155]
	s_waitcnt vmcnt(0) lgkmcnt(0)
	v_lshlrev_b32_e32 v156, 16, v159
	v_and_b32_e32 v157, 0xffff0000, v159
	v_lshlrev_b32_e32 v154, 16, v158
	v_lshlrev_b32_e32 v170, 16, v146
	v_and_b32_e32 v171, 0xffff0000, v146
	v_lshlrev_b32_e32 v172, 16, v147
	v_and_b32_e32 v173, 0xffff0000, v147
	v_lshlrev_b32_e32 v174, 16, v148
	v_and_b32_e32 v175, 0xffff0000, v148
	v_lshlrev_b32_e32 v176, 16, v149
	v_and_b32_e32 v177, 0xffff0000, v149
	v_and_b32_e32 v155, 0xffff0000, v158
	v_lshlrev_b32_e32 v158, 16, v160
	v_and_b32_e32 v159, 0xffff0000, v160
	v_lshlrev_b32_e32 v160, 16, v161
	v_and_b32_e32 v161, 0xffff0000, v161
	s_waitcnt vmcnt(0) lgkmcnt(0)
	v_lshlrev_b32_e32 v162, 16, v150
	v_and_b32_e32 v163, 0xffff0000, v150
	v_lshlrev_b32_e32 v164, 16, v151
	v_and_b32_e32 v165, 0xffff0000, v151
	v_lshlrev_b32_e32 v166, 16, v152
	v_and_b32_e32 v167, 0xffff0000, v152
	v_lshlrev_b32_e32 v168, 16, v153
	v_and_b32_e32 v169, 0xffff0000, v153
	v_lshlrev_b32_e32 v146, 16, v182
	v_and_b32_e32 v147, 0xffff0000, v182
	v_lshlrev_b32_e32 v148, 16, v183
	v_and_b32_e32 v149, 0xffff0000, v183
	v_lshlrev_b32_e32 v150, 16, v184
	v_and_b32_e32 v151, 0xffff0000, v184
	v_lshlrev_b32_e32 v152, 16, v185
	v_and_b32_e32 v153, 0xffff0000, v185
	s_cmp_lt_u32 s68, 2
	s_cbranch_scc1 .Lxr2_0
	v_rcp_f32_e32 v218, v218
	v_rcp_f32_e32 v219, v219
	v_rcp_f32_e32 v220, v220
	v_rcp_f32_e32 v221, v221
	v_rcp_f32_e32 v222, v222
	v_rcp_f32_e32 v223, v223
	v_rcp_f32_e32 v224, v224
	v_rcp_f32_e32 v225, v225
	s_nop 0
	v_pk_mul_f32 v[146:147], v[146:147], v[218:219]
	v_pk_mul_f32 v[148:149], v[148:149], v[220:221]
	v_pk_mul_f32 v[150:151], v[150:151], v[222:223]
	v_pk_mul_f32 v[152:153], v[152:153], v[224:225]
	v_pk_mul_f32 v[154:155], v[154:155], v[218:219]
	v_pk_mul_f32 v[156:157], v[156:157], v[220:221]
	v_pk_mul_f32 v[158:159], v[158:159], v[222:223]
	v_pk_mul_f32 v[160:161], v[160:161], v[224:225]
	v_pk_mul_f32 v[162:163], v[162:163], v[218:219]
	v_pk_mul_f32 v[164:165], v[164:165], v[220:221]
	v_pk_mul_f32 v[166:167], v[166:167], v[222:223]
	v_pk_mul_f32 v[168:169], v[168:169], v[224:225]
	v_pk_mul_f32 v[170:171], v[170:171], v[218:219]
	v_pk_mul_f32 v[172:173], v[172:173], v[220:221]
	v_pk_mul_f32 v[174:175], v[174:175], v[222:223]
	v_pk_mul_f32 v[176:177], v[176:177], v[224:225]

.LBB0_1060:
	v_ashrrev_i32_e32 v205, 31, v204
	s_waitcnt vmcnt(0)
	global_load_dwordx4 v[228:231], v[186:187], off
	global_load_dwordx2 v[234:235], v[186:187], off offset:16
	global_load_dwordx2 v[246:247], v[186:187], off offset:24
	v_lshlrev_b64 v[122:123], 12, v[204:205]
	v_ashrrev_i32_e32 v207, 31, v206
	v_lshl_add_u64 v[122:123], v[226:227], 0, v[122:123]
	v_ashrrev_i32_e32 v203, 31, v202
	v_lshlrev_b64 v[118:119], 12, v[206:207]
	flat_load_dwordx4 v[126:129], v[122:123]
	v_lshlrev_b64 v[122:123], 12, v[202:203]
	v_lshl_add_u64 v[114:115], v[226:227], 0, v[232:233]
	v_lshl_add_u64 v[118:119], v[226:227], 0, v[118:119]
	v_lshl_add_u64 v[122:123], v[226:227], 0, v[122:123]
	flat_load_dwordx4 v[114:117], v[114:115]
	flat_load_dwordx4 v[118:121], v[118:119]
	flat_load_dwordx4 v[182:185], v[122:123]
	s_waitcnt vmcnt(0) lgkmcnt(0)
	v_lshlrev_b32_e32 v124, 16, v127
	v_and_b32_e32 v125, 0xffff0000, v127
	v_lshlrev_b32_e32 v122, 16, v126
	v_lshlrev_b32_e32 v138, 16, v114
	v_and_b32_e32 v139, 0xffff0000, v114
	v_lshlrev_b32_e32 v140, 16, v115
	v_and_b32_e32 v141, 0xffff0000, v115
	v_lshlrev_b32_e32 v142, 16, v116
	v_and_b32_e32 v143, 0xffff0000, v116
	v_lshlrev_b32_e32 v144, 16, v117
	v_and_b32_e32 v145, 0xffff0000, v117
	v_and_b32_e32 v123, 0xffff0000, v126
	v_lshlrev_b32_e32 v126, 16, v128
	v_and_b32_e32 v127, 0xffff0000, v128
	v_lshlrev_b32_e32 v128, 16, v129
	v_and_b32_e32 v129, 0xffff0000, v129
	s_waitcnt vmcnt(0) lgkmcnt(0)
	v_lshlrev_b32_e32 v130, 16, v118
	v_and_b32_e32 v131, 0xffff0000, v118
	v_lshlrev_b32_e32 v132, 16, v119
	v_and_b32_e32 v133, 0xffff0000, v119
	v_lshlrev_b32_e32 v134, 16, v120
	v_and_b32_e32 v135, 0xffff0000, v120
	v_lshlrev_b32_e32 v136, 16, v121
	v_and_b32_e32 v137, 0xffff0000, v121
	v_lshlrev_b32_e32 v114, 16, v182
	v_and_b32_e32 v115, 0xffff0000, v182
	v_lshlrev_b32_e32 v116, 16, v183
	v_and_b32_e32 v117, 0xffff0000, v183
	v_lshlrev_b32_e32 v118, 16, v184
	v_and_b32_e32 v119, 0xffff0000, v184
	v_lshlrev_b32_e32 v120, 16, v185
	v_and_b32_e32 v121, 0xffff0000, v185
	s_cmp_lt_u32 s68, 2
	s_cbranch_scc1 .Lxr2_1
	v_rcp_f32_e32 v228, v228
	v_rcp_f32_e32 v229, v229
	v_rcp_f32_e32 v230, v230
	v_rcp_f32_e32 v231, v231
	v_rcp_f32_e32 v234, v234
	v_rcp_f32_e32 v235, v235
	v_rcp_f32_e32 v246, v246
	v_rcp_f32_e32 v247, v247
	s_nop 0
	v_pk_mul_f32 v[114:115], v[114:115], v[228:229]
	v_pk_mul_f32 v[116:117], v[116:117], v[230:231]
	v_pk_mul_f32 v[118:119], v[118:119], v[234:235]
	v_pk_mul_f32 v[120:121], v[120:121], v[246:247]
	v_pk_mul_f32 v[122:123], v[122:123], v[228:229]
	v_pk_mul_f32 v[124:125], v[124:125], v[230:231]
	v_pk_mul_f32 v[126:127], v[126:127], v[234:235]
	v_pk_mul_f32 v[128:129], v[128:129], v[246:247]
	v_pk_mul_f32 v[130:131], v[130:131], v[228:229]
	v_pk_mul_f32 v[132:133], v[132:133], v[230:231]
	v_pk_mul_f32 v[134:135], v[134:135], v[234:235]
	v_pk_mul_f32 v[136:137], v[136:137], v[246:247]
	v_pk_mul_f32 v[138:139], v[138:139], v[228:229]
	v_pk_mul_f32 v[140:141], v[140:141], v[230:231]
	v_pk_mul_f32 v[142:143], v[142:143], v[234:235]
	v_pk_mul_f32 v[144:145], v[144:145], v[246:247]

.LBB0_1068:
	v_or_b32_e32 v120, 0x80, v196
	v_ashrrev_i32_e32 v121, 31, v120
	s_andn2_b64 vcc, exec, s[30:31]
	v_lshlrev_b64 v[196:197], 1, v[120:121]
	s_cbranch_vccnz .LBB0_1070
	s_waitcnt vmcnt(0)
	global_load_dwordx4 v[208:211], v[186:187], off offset:512
	global_load_dwordx2 v[212:213], v[186:187], off offset:528
	global_load_dwordx2 v[234:235], v[186:187], off offset:536
	v_lshlrev_b64 v[90:91], 12, v[198:199]
	v_lshl_add_u64 v[90:91], s[12:13], 0, v[90:91]
	v_lshl_add_u64 v[90:91], v[90:91], 0, v[196:197]
	v_lshlrev_b64 v[86:87], 12, v[200:201]
	flat_load_dwordx4 v[94:97], v[90:91]
	v_lshlrev_b64 v[90:91], 12, v[194:195]
	v_lshl_add_u64 v[82:83], s[12:13], 0, v[214:215]
	v_lshl_add_u64 v[86:87], s[12:13], 0, v[86:87]
	v_lshl_add_u64 v[90:91], s[12:13], 0, v[90:91]
	v_lshl_add_u64 v[82:83], v[82:83], 0, v[196:197]
	v_lshl_add_u64 v[86:87], v[86:87], 0, v[196:197]
	v_lshl_add_u64 v[90:91], v[90:91], 0, v[196:197]
	flat_load_dwordx4 v[82:85], v[82:83]
	flat_load_dwordx4 v[86:89], v[86:87]
	flat_load_dwordx4 v[182:185], v[90:91]
	s_waitcnt vmcnt(0) lgkmcnt(0)
	v_lshlrev_b32_e32 v92, 16, v95
	v_and_b32_e32 v93, 0xffff0000, v95
	v_lshlrev_b32_e32 v90, 16, v94
	v_and_b32_e32 v91, 0xffff0000, v94
	v_lshlrev_b32_e32 v94, 16, v96
	v_and_b32_e32 v95, 0xffff0000, v96
	v_lshlrev_b32_e32 v106, 16, v82
	v_and_b32_e32 v107, 0xffff0000, v82
	v_lshlrev_b32_e32 v108, 16, v83
	v_and_b32_e32 v109, 0xffff0000, v83
	v_lshlrev_b32_e32 v110, 16, v84
	v_and_b32_e32 v111, 0xffff0000, v84
	v_lshlrev_b32_e32 v112, 16, v85
	v_and_b32_e32 v113, 0xffff0000, v85
	v_lshlrev_b32_e32 v96, 16, v97
	v_and_b32_e32 v97, 0xffff0000, v97
	s_waitcnt vmcnt(0) lgkmcnt(0)
	v_lshlrev_b32_e32 v98, 16, v86
	v_and_b32_e32 v99, 0xffff0000, v86
	v_lshlrev_b32_e32 v100, 16, v87
	v_and_b32_e32 v101, 0xffff0000, v87
	v_lshlrev_b32_e32 v102, 16, v88
	v_and_b32_e32 v103, 0xffff0000, v88
	v_lshlrev_b32_e32 v104, 16, v89
	v_and_b32_e32 v105, 0xffff0000, v89
	v_lshlrev_b32_e32 v82, 16, v182
	v_and_b32_e32 v83, 0xffff0000, v182
	v_lshlrev_b32_e32 v84, 16, v183
	v_and_b32_e32 v85, 0xffff0000, v183
	v_lshlrev_b32_e32 v86, 16, v184
	v_and_b32_e32 v87, 0xffff0000, v184
	v_lshlrev_b32_e32 v88, 16, v185
	v_and_b32_e32 v89, 0xffff0000, v185
	s_cmp_lt_u32 s68, 2
	s_cbranch_scc1 .Lxr2_2
	v_rcp_f32_e32 v208, v208
	v_rcp_f32_e32 v209, v209
	v_rcp_f32_e32 v210, v210
	v_rcp_f32_e32 v211, v211
	v_rcp_f32_e32 v212, v212
	v_rcp_f32_e32 v213, v213
	v_rcp_f32_e32 v234, v234
	v_rcp_f32_e32 v235, v235
	s_nop 0
	v_pk_mul_f32 v[82:83], v[82:83], v[208:209]
	v_pk_mul_f32 v[84:85], v[84:85], v[210:211]
	v_pk_mul_f32 v[86:87], v[86:87], v[212:213]
	v_pk_mul_f32 v[88:89], v[88:89], v[234:235]
	v_pk_mul_f32 v[90:91], v[90:91], v[208:209]
	v_pk_mul_f32 v[92:93], v[92:93], v[210:211]
	v_pk_mul_f32 v[94:95], v[94:95], v[212:213]
	v_pk_mul_f32 v[96:97], v[96:97], v[234:235]
	v_pk_mul_f32 v[98:99], v[98:99], v[208:209]
	v_pk_mul_f32 v[100:101], v[100:101], v[210:211]
	v_pk_mul_f32 v[102:103], v[102:103], v[212:213]
	v_pk_mul_f32 v[104:105], v[104:105], v[234:235]
	v_pk_mul_f32 v[106:107], v[106:107], v[208:209]
	v_pk_mul_f32 v[108:109], v[108:109], v[210:211]
	v_pk_mul_f32 v[110:111], v[110:111], v[212:213]
	v_pk_mul_f32 v[112:113], v[112:113], v[234:235]

.LBB0_1072:
	s_waitcnt vmcnt(0)
	global_load_dwordx4 v[208:211], v[186:187], off offset:512
	global_load_dwordx4 v[212:215], v[186:187], off offset:528
	v_lshlrev_b64 v[42:43], 12, v[204:205]
	v_lshl_add_u64 v[42:43], s[12:13], 0, v[42:43]
	v_lshl_add_u64 v[42:43], v[42:43], 0, v[196:197]
	v_lshlrev_b64 v[38:39], 12, v[206:207]
	flat_load_dwordx4 v[46:49], v[42:43]
	v_lshlrev_b64 v[42:43], 12, v[202:203]
	v_lshl_add_u64 v[34:35], s[12:13], 0, v[232:233]
	v_lshl_add_u64 v[38:39], s[12:13], 0, v[38:39]
	v_lshl_add_u64 v[42:43], s[12:13], 0, v[42:43]
	v_lshl_add_u64 v[34:35], v[34:35], 0, v[196:197]
	v_lshl_add_u64 v[38:39], v[38:39], 0, v[196:197]
	v_lshl_add_u64 v[42:43], v[42:43], 0, v[196:197]
	flat_load_dwordx4 v[34:37], v[34:35]
	flat_load_dwordx4 v[38:41], v[38:39]
	flat_load_dwordx4 v[182:185], v[42:43]
	s_waitcnt vmcnt(0) lgkmcnt(0)
	v_lshlrev_b32_e32 v44, 16, v47
	v_and_b32_e32 v45, 0xffff0000, v47
	v_lshlrev_b32_e32 v42, 16, v46
	v_and_b32_e32 v43, 0xffff0000, v46
	v_lshlrev_b32_e32 v46, 16, v48
	v_and_b32_e32 v47, 0xffff0000, v48
	v_lshlrev_b32_e32 v58, 16, v34
	v_and_b32_e32 v59, 0xffff0000, v34
	v_lshlrev_b32_e32 v60, 16, v35
	v_and_b32_e32 v61, 0xffff0000, v35
	v_lshlrev_b32_e32 v62, 16, v36
	v_and_b32_e32 v63, 0xffff0000, v36
	v_lshlrev_b32_e32 v64, 16, v37
	v_and_b32_e32 v65, 0xffff0000, v37
	v_lshlrev_b32_e32 v48, 16, v49
	v_and_b32_e32 v49, 0xffff0000, v49
	s_waitcnt vmcnt(0) lgkmcnt(0)
	v_lshlrev_b32_e32 v50, 16, v38
	v_and_b32_e32 v51, 0xffff0000, v38
	v_lshlrev_b32_e32 v52, 16, v39
	v_and_b32_e32 v53, 0xffff0000, v39
	v_lshlrev_b32_e32 v54, 16, v40
	v_and_b32_e32 v55, 0xffff0000, v40
	v_lshlrev_b32_e32 v56, 16, v41
	v_and_b32_e32 v57, 0xffff0000, v41
	v_lshlrev_b32_e32 v34, 16, v182
	v_and_b32_e32 v35, 0xffff0000, v182
	v_lshlrev_b32_e32 v36, 16, v183
	v_and_b32_e32 v37, 0xffff0000, v183
	v_lshlrev_b32_e32 v38, 16, v184
	v_and_b32_e32 v39, 0xffff0000, v184
	v_lshlrev_b32_e32 v40, 16, v185
	v_and_b32_e32 v41, 0xffff0000, v185
	s_cmp_lt_u32 s68, 2
	s_cbranch_scc1 .Lxr2_3
	v_rcp_f32_e32 v208, v208
	v_rcp_f32_e32 v209, v209
	v_rcp_f32_e32 v210, v210
	v_rcp_f32_e32 v211, v211
	v_rcp_f32_e32 v212, v212
	v_rcp_f32_e32 v213, v213
	v_rcp_f32_e32 v214, v214
	v_rcp_f32_e32 v215, v215
	s_nop 0
	v_pk_mul_f32 v[34:35], v[34:35], v[208:209]
	v_pk_mul_f32 v[36:37], v[36:37], v[210:211]
	v_pk_mul_f32 v[38:39], v[38:39], v[212:213]
	v_pk_mul_f32 v[40:41], v[40:41], v[214:215]
	v_pk_mul_f32 v[42:43], v[42:43], v[208:209]
	v_pk_mul_f32 v[44:45], v[44:45], v[210:211]
	v_pk_mul_f32 v[46:47], v[46:47], v[212:213]
	v_pk_mul_f32 v[48:49], v[48:49], v[214:215]
	v_pk_mul_f32 v[50:51], v[50:51], v[208:209]
	v_pk_mul_f32 v[52:53], v[52:53], v[210:211]
	v_pk_mul_f32 v[54:55], v[54:55], v[212:213]
	v_pk_mul_f32 v[56:57], v[56:57], v[214:215]
	v_pk_mul_f32 v[58:59], v[58:59], v[208:209]
	v_pk_mul_f32 v[60:61], v[60:61], v[210:211]
	v_pk_mul_f32 v[62:63], v[62:63], v[212:213]
	v_pk_mul_f32 v[64:65], v[64:65], v[214:215]
